# best_v22 plus nt (streaming) policy on the prologue once-read f32 weight and x loads
# baseline (speedup 1.0000x reference)
; #define LAS __attribute__((address_space(3)))
; template <int MAP> __device__ __forceinline__ void transpose_item(const float* __restrict__ W, const float* __restrict__ gk, int K, int N, u16* __restrict__ WT, LAS float* scr, int item, int lane) {
;     const int nblk = (N + 31) >> 5, kb = item / nblk, nb = item - kb * nblk, k0 = 64 * kb, n0 = 32 * nb;
;     const int nn = n0 + (lane & 31); const bool ok = nn < N;
;     float wv[32];
; #pragma unroll
;     for (int i = 0; i < 32; ++i) { const int kk = 2 * i + (lane >> 5); wv[i] = ok ? W[(size_t)(k0 + kk) * N + nn] : 0.f; }
.LBB0_15:
	s_mul_hi_i32 s0, s23, 0x2e8ba2e9
	s_lshr_b32 s1, s0, 31
	s_ashr_i32 s0, s0, 5
	s_add_i32 s62, s0, s1
	s_mul_i32 s69, s62, 0xffffea00
	s_add_i32 s0, s69, s68
	v_add_u32_e32 v12, s0, v33
	s_lshl_b32 s64, s62, 6
	v_ashrrev_i32_e32 v13, 31, v12
	v_cmp_gt_i32_e32 vcc, s73, v12
	v_or_b32_e32 v14, s64, v6
	v_lshl_add_u64 v[20:21], v[12:13], 2, s[60:61]
	v_mov_b32_e32 v8, 0
	v_mov_b32_e32 v56, 0
	s_and_saveexec_b64 s[0:1], vcc
	s_cbranch_execz .LBB0_17
	v_mad_i64_i32 v[12:13], s[66:67], v14, s74, v[20:21]
	global_load_dword v56, v[12:13], off nt
.LBB0_17:
	s_or_b64 exec, exec, s[0:1]
	s_and_saveexec_b64 s[0:1], vcc
	s_cbranch_execz .LBB0_19
	v_or_b32_e32 v8, 2, v14
	v_mad_i64_i32 v[12:13], s[66:67], v8, s74, v[20:21]
	global_load_dword v8, v[12:13], off nt
.LBB0_19:
	s_or_b64 exec, exec, s[0:1]
	v_mov_b32_e32 v59, 0
	v_mov_b32_e32 v60, 0
	s_and_saveexec_b64 s[0:1], vcc
	s_cbranch_execz .LBB0_21
	v_or_b32_e32 v12, 4, v14
	v_mad_i64_i32 v[12:13], s[66:67], v12, s74, v[20:21]
	global_load_dword v60, v[12:13], off nt
.LBB0_21:
	s_or_b64 exec, exec, s[0:1]
	s_and_saveexec_b64 s[0:1], vcc
	s_cbranch_execz .LBB0_23
	v_or_b32_e32 v12, 6, v14
	v_mad_i64_i32 v[12:13], s[66:67], v12, s74, v[20:21]
	global_load_dword v59, v[12:13], off nt
.LBB0_23:
	s_or_b64 exec, exec, s[0:1]
	v_mov_b32_e32 v13, 0
	v_mov_b32_e32 v12, 0
	s_and_saveexec_b64 s[0:1], vcc
	s_cbranch_execz .LBB0_25
	v_or_b32_e32 v12, 8, v14
	v_mad_i64_i32 v[16:17], s[66:67], v12, s74, v[20:21]
	global_load_dword v12, v[16:17], off nt
.LBB0_25:
	s_or_b64 exec, exec, s[0:1]
	s_and_saveexec_b64 s[0:1], vcc
	s_cbranch_execz .LBB0_27
	v_or_b32_e32 v13, 10, v14
	v_mad_i64_i32 v[16:17], s[66:67], v13, s74, v[20:21]
	global_load_dword v13, v[16:17], off nt
.LBB0_27:
	s_or_b64 exec, exec, s[0:1]
	v_mov_b32_e32 v19, 0
	v_mov_b32_e32 v18, 0
	s_and_saveexec_b64 s[0:1], vcc
	s_cbranch_execz .LBB0_29
	v_or_b32_e32 v15, 12, v14
	v_mad_i64_i32 v[16:17], s[66:67], v15, s74, v[20:21]
	global_load_dword v18, v[16:17], off nt
.LBB0_29:
	s_or_b64 exec, exec, s[0:1]
	s_and_saveexec_b64 s[0:1], vcc
	s_cbranch_execz .LBB0_31
	v_or_b32_e32 v15, 14, v14
	v_mad_i64_i32 v[16:17], s[66:67], v15, s74, v[20:21]
	global_load_dword v19, v[16:17], off nt
.LBB0_31:
	s_or_b64 exec, exec, s[0:1]
	v_mov_b32_e32 v57, 0
	v_mov_b32_e32 v58, 0
	s_and_saveexec_b64 s[0:1], vcc
	s_cbranch_execz .LBB0_33
	v_or_b32_e32 v15, 16, v14
	v_mad_i64_i32 v[16:17], s[66:67], v15, s74, v[20:21]
	global_load_dword v58, v[16:17], off nt
.LBB0_33:
	s_or_b64 exec, exec, s[0:1]
	s_and_saveexec_b64 s[0:1], vcc
	s_cbranch_execz .LBB0_35
	v_or_b32_e32 v15, 18, v14
	v_mad_i64_i32 v[16:17], s[66:67], v15, s74, v[20:21]
	global_load_dword v57, v[16:17], off nt
.LBB0_35:
	s_or_b64 exec, exec, s[0:1]
	v_mov_b32_e32 v63, 0
	v_mov_b32_e32 v64, 0
	s_and_saveexec_b64 s[0:1], vcc
	s_cbranch_execz .LBB0_37
	v_or_b32_e32 v15, 20, v14
	v_mad_i64_i32 v[16:17], s[66:67], v15, s74, v[20:21]
	global_load_dword v64, v[16:17], off nt
.LBB0_37:
	s_or_b64 exec, exec, s[0:1]
	s_and_saveexec_b64 s[0:1], vcc
	s_cbranch_execz .LBB0_39
	v_or_b32_e32 v15, 22, v14
	v_mad_i64_i32 v[16:17], s[66:67], v15, s74, v[20:21]
	global_load_dword v63, v[16:17], off nt
.LBB0_39:
	s_or_b64 exec, exec, s[0:1]
	v_mov_b32_e32 v17, 0
	v_mov_b32_e32 v16, 0
	s_and_saveexec_b64 s[0:1], vcc
	s_cbranch_execz .LBB0_41
	v_or_b32_e32 v15, 24, v14
	v_mad_i64_i32 v[22:23], s[66:67], v15, s74, v[20:21]
	global_load_dword v16, v[22:23], off nt
.LBB0_41:
	s_or_b64 exec, exec, s[0:1]
	s_and_saveexec_b64 s[0:1], vcc
	s_cbranch_execz .LBB0_43
	v_or_b32_e32 v15, 26, v14
	v_mad_i64_i32 v[22:23], s[66:67], v15, s74, v[20:21]
	global_load_dword v17, v[22:23], off nt
.LBB0_43:
	s_or_b64 exec, exec, s[0:1]
	v_mov_b32_e32 v25, 0
	v_mov_b32_e32 v24, 0
	s_and_saveexec_b64 s[0:1], vcc
	s_cbranch_execz .LBB0_45
	v_or_b32_e32 v15, 28, v14
	v_mad_i64_i32 v[22:23], s[66:67], v15, s74, v[20:21]
	global_load_dword v24, v[22:23], off nt
.LBB0_45:
	s_or_b64 exec, exec, s[0:1]
	s_and_saveexec_b64 s[0:1], vcc
	s_cbranch_execz .LBB0_47
	v_or_b32_e32 v15, 30, v14
	v_mad_i64_i32 v[22:23], s[66:67], v15, s74, v[20:21]
	global_load_dword v25, v[22:23], off nt
.LBB0_47:
	s_or_b64 exec, exec, s[0:1]
	v_mov_b32_e32 v61, 0
	v_mov_b32_e32 v62, 0
	s_and_saveexec_b64 s[0:1], vcc
	s_cbranch_execz .LBB0_49
	v_or_b32_e32 v15, 32, v14
	v_mad_i64_i32 v[22:23], s[66:67], v15, s74, v[20:21]
	global_load_dword v62, v[22:23], off nt
.LBB0_49:
	s_or_b64 exec, exec, s[0:1]
	s_and_saveexec_b64 s[0:1], vcc
	s_cbranch_execz .LBB0_51
	v_or_b32_e32 v15, 34, v14
	v_mad_i64_i32 v[22:23], s[66:67], v15, s74, v[20:21]
	global_load_dword v61, v[22:23], off nt
; template <int MAP> __device__ __forceinline__ void transpose_item(const float* __restrict__ W, const float* __restrict__ gk, int K, int N, u16* __restrict__ WT, LAS float* scr, int item, int lane) {
;     ...
;     for (int i = 0; i < 32; ++i) { const int kk = 2 * i + (lane >> 5); wv[i] = ok ? W[(size_t)(k0 + kk) * N + nn] : 0.f; }
; #pragma unroll
;     for (int i = 0; i < 32; ++i) { const int kk = 2 * i + (lane >> 5); float w = wv[i]; if (gk) w *= gk[k0 + kk]; scr[kk * 33 + (lane & 31)] = w; }
.LBB0_51:
	s_or_b64 exec, exec, s[0:1]
	v_mov_b32_e32 v67, 0
	v_mov_b32_e32 v68, 0
	s_and_saveexec_b64 s[0:1], vcc
	s_cbranch_execz .LBB0_53
	v_or_b32_e32 v15, 36, v14
	v_mad_i64_i32 v[22:23], s[66:67], v15, s74, v[20:21]
	global_load_dword v68, v[22:23], off nt
.LBB0_53:
	s_or_b64 exec, exec, s[0:1]
	s_and_saveexec_b64 s[0:1], vcc
	s_cbranch_execz .LBB0_55
	v_or_b32_e32 v15, 38, v14
	v_mad_i64_i32 v[22:23], s[66:67], v15, s74, v[20:21]
	global_load_dword v67, v[22:23], off nt
.LBB0_55:
	s_or_b64 exec, exec, s[0:1]
	v_mov_b32_e32 v23, 0
	v_mov_b32_e32 v22, 0
	s_and_saveexec_b64 s[0:1], vcc
	s_cbranch_execz .LBB0_57
	v_or_b32_e32 v15, 40, v14
	v_mad_i64_i32 v[26:27], s[66:67], v15, s74, v[20:21]
	global_load_dword v22, v[26:27], off nt
.LBB0_57:
	s_or_b64 exec, exec, s[0:1]
	s_and_saveexec_b64 s[0:1], vcc
	s_cbranch_execz .LBB0_59
	v_or_b32_e32 v15, 42, v14
	v_mad_i64_i32 v[26:27], s[66:67], v15, s74, v[20:21]
	global_load_dword v23, v[26:27], off nt
.LBB0_59:
	s_or_b64 exec, exec, s[0:1]
	v_mov_b32_e32 v29, 0
	v_mov_b32_e32 v28, 0
	s_and_saveexec_b64 s[0:1], vcc
	s_cbranch_execz .LBB0_61
	v_or_b32_e32 v15, 44, v14
	v_mad_i64_i32 v[26:27], s[66:67], v15, s74, v[20:21]
	global_load_dword v28, v[26:27], off nt
.LBB0_61:
	s_or_b64 exec, exec, s[0:1]
	s_and_saveexec_b64 s[0:1], vcc
	s_cbranch_execz .LBB0_63
	v_or_b32_e32 v15, 46, v14
	v_mad_i64_i32 v[26:27], s[66:67], v15, s74, v[20:21]
	global_load_dword v29, v[26:27], off nt
.LBB0_63:
	s_or_b64 exec, exec, s[0:1]
	v_mov_b32_e32 v65, 0
	v_mov_b32_e32 v66, 0
	s_and_saveexec_b64 s[0:1], vcc
	s_cbranch_execz .LBB0_65
	v_or_b32_e32 v15, 48, v14
	v_mad_i64_i32 v[26:27], s[66:67], v15, s74, v[20:21]
	global_load_dword v66, v[26:27], off nt
.LBB0_65:
	s_or_b64 exec, exec, s[0:1]
	s_and_saveexec_b64 s[0:1], vcc
	s_cbranch_execz .LBB0_67
	v_or_b32_e32 v15, 50, v14
	v_mad_i64_i32 v[26:27], s[66:67], v15, s74, v[20:21]
	global_load_dword v65, v[26:27], off nt
.LBB0_67:
	s_or_b64 exec, exec, s[0:1]
	v_mov_b32_e32 v69, 0
	v_mov_b32_e32 v70, 0
	s_and_saveexec_b64 s[0:1], vcc
	s_cbranch_execz .LBB0_69
	v_or_b32_e32 v15, 52, v14
	v_mad_i64_i32 v[26:27], s[66:67], v15, s74, v[20:21]
	global_load_dword v70, v[26:27], off nt
.LBB0_69:
	s_or_b64 exec, exec, s[0:1]
	s_and_saveexec_b64 s[0:1], vcc
	s_cbranch_execz .LBB0_71
	v_or_b32_e32 v15, 54, v14
	v_mad_i64_i32 v[26:27], s[66:67], v15, s74, v[20:21]
	global_load_dword v69, v[26:27], off nt
.LBB0_71:
	s_or_b64 exec, exec, s[0:1]
	v_mov_b32_e32 v27, 0
	v_mov_b32_e32 v26, 0
	s_and_saveexec_b64 s[0:1], vcc
	s_cbranch_execz .LBB0_73
	v_or_b32_e32 v15, 56, v14
	v_mad_i64_i32 v[30:31], s[66:67], v15, s74, v[20:21]
	global_load_dword v26, v[30:31], off nt
.LBB0_73:
	s_or_b64 exec, exec, s[0:1]
	s_and_saveexec_b64 s[0:1], vcc
	s_cbranch_execz .LBB0_75
	v_or_b32_e32 v15, 58, v14
	v_mad_i64_i32 v[30:31], s[66:67], v15, s74, v[20:21]
	global_load_dword v27, v[30:31], off nt
.LBB0_75:
	s_or_b64 exec, exec, s[0:1]
	v_mov_b32_e32 v31, 0
	v_mov_b32_e32 v30, 0
	s_and_saveexec_b64 s[0:1], vcc
	s_cbranch_execz .LBB0_77
	v_or_b32_e32 v15, 60, v14
	v_mad_i64_i32 v[72:73], s[66:67], v15, s74, v[20:21]
	global_load_dword v30, v[72:73], off nt
.LBB0_77:
	s_or_b64 exec, exec, s[0:1]
	s_and_saveexec_b64 s[0:1], vcc
	s_cbranch_execz .LBB0_79
	v_or_b32_e32 v15, 62, v14
	v_mad_i64_i32 v[20:21], s[66:67], v15, s74, v[20:21]
	global_load_dword v31, v[20:21], off nt
.LBB0_79:
	s_or_b64 exec, exec, s[0:1]
	v_cndmask_b32_e64 v15, 0, 1, s[48:49]
	v_cmp_ne_u32_e64 s[0:1], 1, v15
	s_andn2_b64 vcc, exec, s[48:49]
	s_cbranch_vccnz .LBB0_99
	v_ashrrev_i32_e32 v15, 31, v14
	s_ashr_i32 s65, s64, 31
	v_lshl_add_u64 v[14:15], v[14:15], 2, s[58:59]
	v_lshl_add_u64 v[20:21], s[64:65], 0, v[6:7]
	v_lshl_add_u64 v[20:21], v[20:21], 2, s[58:59]
	global_load_dword v71, v[14:15], off nt
	global_load_dword v78, v[20:21], off offset:8 nt
	global_load_dword v79, v[20:21], off offset:16 nt
	global_load_dword v80, v[20:21], off offset:24 nt
	s_nop 0
	global_load_dword v14, v[20:21], off offset:32 nt
	global_load_dword v15, v[20:21], off offset:40 nt
	global_load_dword v72, v[20:21], off offset:48 nt
	global_load_dword v73, v[20:21], off offset:56 nt
	v_add_u32_e32 v81, v35, v37
	s_waitcnt vmcnt(7)
	v_mul_f32_e32 v20, v56, v71
	s_waitcnt vmcnt(6)
	v_mul_f32_e32 v71, v8, v78
	s_waitcnt vmcnt(5)
	v_mul_f32_e32 v78, v60, v79
	ds_write_b32 v36, v20
	s_waitcnt vmcnt(4)
	v_mul_f32_e32 v79, v59, v80
	s_waitcnt vmcnt(2)
	v_pk_mul_f32 v[14:15], v[12:13], v[14:15]
	ds_write2_b32 v81, v71, v78 offset1:66
	ds_write_b32 v81, v79 offset:528
	s_waitcnt vmcnt(0)
	v_pk_mul_f32 v[20:21], v[18:19], v[72:73]
	s_cbranch_execnz .LBB0_82

; template <int MAP> __device__ __forceinline__ void transpose_item(const float* __restrict__ W, const float* __restrict__ gk, int K, int N, u16* __restrict__ WT, LAS float* scr, int item, int lane) {
;     ...
; #pragma unroll
;     for (int i = 0; i < 32; ++i) { const int kk = 2 * i + (lane >> 5); float w = wv[i]; if (gk) w *= gk[k0 + kk]; scr[kk * 33 + (lane & 31)] = w; }
.LBB0_82:
	s_waitcnt vmcnt(0)
	v_add_u32_e32 v8, v35, v38
	s_and_b64 vcc, exec, s[0:1]
	ds_write2_b32 v8, v14, v15 offset1:66
	ds_write2_b32 v8, v20, v21 offset0:132 offset1:198
	s_cbranch_vccnz .LBB0_100
	s_ashr_i32 s65, s64, 31
	v_lshl_add_u64 v[12:13], s[64:65], 0, v[6:7]
	v_lshl_add_u64 v[12:13], v[12:13], 2, s[58:59]
	global_load_dword v8, v[12:13], off offset:64 nt
	global_load_dword v20, v[12:13], off offset:72 nt
	global_load_dword v21, v[12:13], off offset:80 nt
	global_load_dword v56, v[12:13], off offset:88 nt
	global_load_dword v14, v[12:13], off offset:96 nt
	global_load_dword v15, v[12:13], off offset:104 nt
	global_load_dword v18, v[12:13], off offset:112 nt
	global_load_dword v19, v[12:13], off offset:120 nt
	v_add_u32_e32 v59, v35, v39
	s_waitcnt vmcnt(7)
	v_mul_f32_e32 v8, v58, v8
	s_waitcnt vmcnt(6)
	v_mul_f32_e32 v20, v57, v20
	s_waitcnt vmcnt(5)
	v_mul_f32_e32 v21, v64, v21
	s_waitcnt vmcnt(4)
	v_mul_f32_e32 v56, v63, v56
	ds_write2_b32 v59, v8, v20 offset1:66
	ds_write2_b32 v59, v21, v56 offset0:132 offset1:198
	s_waitcnt vmcnt(2)
	v_pk_mul_f32 v[12:13], v[16:17], v[14:15]
	s_waitcnt vmcnt(0)
	v_pk_mul_f32 v[14:15], v[24:25], v[18:19]
	s_cbranch_execnz .LBB0_85

; template <int MAP> __device__ __forceinline__ void transpose_item(const float* __restrict__ W, const float* __restrict__ gk, int K, int N, u16* __restrict__ WT, LAS float* scr, int item, int lane) {
;     ...
; #pragma unroll
;     for (int i = 0; i < 32; ++i) { const int kk = 2 * i + (lane >> 5); float w = wv[i]; if (gk) w *= gk[k0 + kk]; scr[kk * 33 + (lane & 31)] = w; }
.LBB0_85:
	v_add_u32_e32 v8, v35, v40
	s_and_b64 vcc, exec, s[0:1]
	ds_write2_b32 v8, v12, v13 offset1:66
	ds_write2_b32 v8, v14, v15 offset0:132 offset1:198
	s_cbranch_vccnz .LBB0_101
	s_ashr_i32 s65, s64, 31
	v_lshl_add_u64 v[12:13], s[64:65], 0, v[6:7]
	v_lshl_add_u64 v[12:13], v[12:13], 2, s[58:59]
	global_load_dword v8, v[12:13], off offset:128 nt
	global_load_dword v18, v[12:13], off offset:136 nt
	global_load_dword v19, v[12:13], off offset:144 nt
	global_load_dword v20, v[12:13], off offset:152 nt
	global_load_dword v14, v[12:13], off offset:160 nt
	global_load_dword v15, v[12:13], off offset:168 nt
	global_load_dword v16, v[12:13], off offset:176 nt
	global_load_dword v17, v[12:13], off offset:184 nt
	v_add_u32_e32 v21, v35, v41
	s_waitcnt vmcnt(7)
	v_mul_f32_e32 v8, v62, v8
	s_waitcnt vmcnt(6)
	v_mul_f32_e32 v18, v61, v18
	s_waitcnt vmcnt(5)
	v_mul_f32_e32 v19, v68, v19
	s_waitcnt vmcnt(4)
	v_mul_f32_e32 v20, v67, v20
	ds_write2_b32 v21, v8, v18 offset1:66
	ds_write2_b32 v21, v19, v20 offset0:132 offset1:198
	s_waitcnt vmcnt(2)
	v_pk_mul_f32 v[12:13], v[22:23], v[14:15]
	s_waitcnt vmcnt(0)
	v_pk_mul_f32 v[14:15], v[28:29], v[16:17]
	s_cbranch_execnz .LBB0_88

; template <int MAP> __device__ __forceinline__ void transpose_item(const float* __restrict__ W, const float* __restrict__ gk, int K, int N, u16* __restrict__ WT, LAS float* scr, int item, int lane) {
;     ...
; #pragma unroll
;     for (int i = 0; i < 32; ++i) { const int kk = 2 * i + (lane >> 5); float w = wv[i]; if (gk) w *= gk[k0 + kk]; scr[kk * 33 + (lane & 31)] = w; }
.LBB0_88:
	v_add_u32_e32 v8, v35, v42
	s_and_b64 vcc, exec, s[0:1]
	ds_write2_b32 v8, v12, v13 offset1:66
	ds_write2_b32 v8, v14, v15 offset0:132 offset1:198
	s_cbranch_vccnz .LBB0_102
	s_ashr_i32 s65, s64, 31
	v_lshl_add_u64 v[12:13], s[64:65], 0, v[6:7]
	v_lshl_add_u64 v[12:13], v[12:13], 2, s[58:59]
	global_load_dword v8, v[12:13], off offset:192 nt
	global_load_dword v18, v[12:13], off offset:200 nt
	global_load_dword v19, v[12:13], off offset:208 nt
	global_load_dword v20, v[12:13], off offset:216 nt
	global_load_dword v14, v[12:13], off offset:224 nt
	global_load_dword v15, v[12:13], off offset:232 nt
	global_load_dword v16, v[12:13], off offset:240 nt
	global_load_dword v17, v[12:13], off offset:248 nt
	v_add_u32_e32 v21, v35, v43
	s_waitcnt vmcnt(7)
	v_mul_f32_e32 v8, v66, v8
	s_waitcnt vmcnt(6)
	v_mul_f32_e32 v18, v65, v18
	s_waitcnt vmcnt(5)
	v_mul_f32_e32 v19, v70, v19
	s_waitcnt vmcnt(4)
	v_mul_f32_e32 v20, v69, v20
	ds_write2_b32 v21, v8, v18 offset1:66
	ds_write2_b32 v21, v19, v20 offset0:132 offset1:198
	s_waitcnt vmcnt(2)
	v_pk_mul_f32 v[12:13], v[26:27], v[14:15]
	s_waitcnt vmcnt(0)
	v_pk_mul_f32 v[14:15], v[30:31], v[16:17]
	s_cbranch_execnz .LBB0_91

; #define LAS __attribute__((address_space(3)))
; template <int MAP> __device__ __forceinline__ void transpose_item(const float* __restrict__ W, const float* __restrict__ gk, int K, int N, u16* __restrict__ WT, LAS float* scr, int item, int lane) {
;     const int nblk = (N + 31) >> 5, kb = item / nblk, nb = item - kb * nblk, k0 = 64 * kb, n0 = 32 * nb;
;     const int nn = n0 + (lane & 31); const bool ok = nn < N;
;     float wv[32];
; #pragma unroll
;     for (int i = 0; i < 32; ++i) { const int kk = 2 * i + (lane >> 5); wv[i] = ok ? W[(size_t)(k0 + kk) * N + nn] : 0.f; }
.LBB0_106:
	s_ashr_i32 s22, s61, 31
	s_lshr_b32 s22, s22, 27
	s_add_i32 s22, s61, s22
	s_ashr_i32 s58, s22, 5
	s_lshl_b32 s59, s58, 10
	s_sub_i32 s22, s63, s59
	v_add_u32_e32 v14, s22, v34
	v_ashrrev_i32_e32 v15, 31, v14
	v_cmp_gt_i32_e32 vcc, s79, v14
	v_lshl_or_b32 v16, s58, 6, v6
	v_lshl_add_u64 v[14:15], v[14:15], 2, s[0:1]
	v_mov_b32_e32 v18, 0
	v_mov_b32_e32 v8, 0
	s_and_saveexec_b64 s[22:23], vcc
	s_cbranch_execz .LBB0_108
	v_ashrrev_i32_e32 v17, 31, v16
	v_lshlrev_b64 v[20:21], 12, v[16:17]
	v_lshl_add_u64 v[20:21], v[14:15], 0, v[20:21]
	global_load_dword v8, v[20:21], off nt
.LBB0_108:
	s_or_b64 exec, exec, s[22:23]
	s_and_saveexec_b64 s[22:23], vcc
	s_cbranch_execz .LBB0_110
	v_or_b32_e32 v18, 2, v16
	v_ashrrev_i32_e32 v19, 31, v18
	v_lshlrev_b64 v[18:19], 12, v[18:19]
	v_lshl_add_u64 v[18:19], v[14:15], 0, v[18:19]
	global_load_dword v18, v[18:19], off nt
.LBB0_110:
	s_or_b64 exec, exec, s[22:23]
	v_mov_b32_e32 v17, 0
	v_mov_b32_e32 v19, 0
	s_and_saveexec_b64 s[22:23], vcc
	s_cbranch_execz .LBB0_112
	v_or_b32_e32 v20, 4, v16
	v_ashrrev_i32_e32 v21, 31, v20
	v_lshlrev_b64 v[20:21], 12, v[20:21]
	v_lshl_add_u64 v[20:21], v[14:15], 0, v[20:21]
	global_load_dword v19, v[20:21], off nt
.LBB0_112:
	s_or_b64 exec, exec, s[22:23]
	s_and_saveexec_b64 s[22:23], vcc
	s_cbranch_execz .LBB0_114
	v_or_b32_e32 v20, 6, v16
	v_ashrrev_i32_e32 v21, 31, v20
	v_lshlrev_b64 v[20:21], 12, v[20:21]
	v_lshl_add_u64 v[20:21], v[14:15], 0, v[20:21]
	global_load_dword v17, v[20:21], off nt
.LBB0_114:
	s_or_b64 exec, exec, s[22:23]
	v_mov_b32_e32 v20, 0
	v_mov_b32_e32 v21, 0
	s_and_saveexec_b64 s[22:23], vcc
	s_cbranch_execz .LBB0_116
	v_or_b32_e32 v22, 8, v16
	v_ashrrev_i32_e32 v23, 31, v22
	v_lshlrev_b64 v[22:23], 12, v[22:23]
	v_lshl_add_u64 v[22:23], v[14:15], 0, v[22:23]
	global_load_dword v21, v[22:23], off nt
.LBB0_116:
	s_or_b64 exec, exec, s[22:23]
	s_and_saveexec_b64 s[22:23], vcc
	s_cbranch_execz .LBB0_118
	v_or_b32_e32 v22, 10, v16
	v_ashrrev_i32_e32 v23, 31, v22
	v_lshlrev_b64 v[22:23], 12, v[22:23]
	v_lshl_add_u64 v[22:23], v[14:15], 0, v[22:23]
	global_load_dword v20, v[22:23], off nt
.LBB0_118:
	s_or_b64 exec, exec, s[22:23]
	v_mov_b32_e32 v22, 0
	v_mov_b32_e32 v23, 0
	s_and_saveexec_b64 s[22:23], vcc
	s_cbranch_execz .LBB0_120
	v_or_b32_e32 v24, 12, v16
	v_ashrrev_i32_e32 v25, 31, v24
	v_lshlrev_b64 v[24:25], 12, v[24:25]
	v_lshl_add_u64 v[24:25], v[14:15], 0, v[24:25]
	global_load_dword v23, v[24:25], off nt
.LBB0_120:
	s_or_b64 exec, exec, s[22:23]
	s_and_saveexec_b64 s[22:23], vcc
	s_cbranch_execz .LBB0_122
	v_or_b32_e32 v24, 14, v16
	v_ashrrev_i32_e32 v25, 31, v24
	v_lshlrev_b64 v[24:25], 12, v[24:25]
	v_lshl_add_u64 v[24:25], v[14:15], 0, v[24:25]
	global_load_dword v22, v[24:25], off nt
.LBB0_122:
	s_or_b64 exec, exec, s[22:23]
	v_mov_b32_e32 v24, 0
	v_mov_b32_e32 v25, 0
	s_and_saveexec_b64 s[22:23], vcc
	s_cbranch_execz .LBB0_124
	v_or_b32_e32 v26, 16, v16
	v_ashrrev_i32_e32 v27, 31, v26
	v_lshlrev_b64 v[26:27], 12, v[26:27]
	v_lshl_add_u64 v[26:27], v[14:15], 0, v[26:27]
	global_load_dword v25, v[26:27], off nt
.LBB0_124:
	s_or_b64 exec, exec, s[22:23]
	s_and_saveexec_b64 s[22:23], vcc
	s_cbranch_execz .LBB0_126
	v_or_b32_e32 v26, 18, v16
	v_ashrrev_i32_e32 v27, 31, v26
	v_lshlrev_b64 v[26:27], 12, v[26:27]
	v_lshl_add_u64 v[26:27], v[14:15], 0, v[26:27]
	global_load_dword v24, v[26:27], off nt
.LBB0_126:
	s_or_b64 exec, exec, s[22:23]
	v_mov_b32_e32 v26, 0
	v_mov_b32_e32 v27, 0
	s_and_saveexec_b64 s[22:23], vcc
	s_cbranch_execz .LBB0_128
	v_or_b32_e32 v28, 20, v16
	v_ashrrev_i32_e32 v29, 31, v28
	v_lshlrev_b64 v[28:29], 12, v[28:29]
	v_lshl_add_u64 v[28:29], v[14:15], 0, v[28:29]
	global_load_dword v27, v[28:29], off nt
.LBB0_128:
	s_or_b64 exec, exec, s[22:23]
	s_and_saveexec_b64 s[22:23], vcc
	s_cbranch_execz .LBB0_130
	v_or_b32_e32 v28, 22, v16
	v_ashrrev_i32_e32 v29, 31, v28
	v_lshlrev_b64 v[28:29], 12, v[28:29]
	v_lshl_add_u64 v[28:29], v[14:15], 0, v[28:29]
	global_load_dword v26, v[28:29], off nt
.LBB0_130:
	s_or_b64 exec, exec, s[22:23]
	v_mov_b32_e32 v28, 0
	v_mov_b32_e32 v29, 0
	s_and_saveexec_b64 s[22:23], vcc
	s_cbranch_execz .LBB0_132
	v_or_b32_e32 v30, 24, v16
	v_ashrrev_i32_e32 v31, 31, v30
	v_lshlrev_b64 v[30:31], 12, v[30:31]
	v_lshl_add_u64 v[30:31], v[14:15], 0, v[30:31]
	global_load_dword v29, v[30:31], off nt
.LBB0_132:
	s_or_b64 exec, exec, s[22:23]
	s_and_saveexec_b64 s[22:23], vcc
	s_cbranch_execz .LBB0_134
	v_or_b32_e32 v30, 26, v16
	v_ashrrev_i32_e32 v31, 31, v30
	v_lshlrev_b64 v[30:31], 12, v[30:31]
	v_lshl_add_u64 v[30:31], v[14:15], 0, v[30:31]
	global_load_dword v28, v[30:31], off nt
.LBB0_134:
	s_or_b64 exec, exec, s[22:23]
	v_mov_b32_e32 v30, 0
	v_mov_b32_e32 v31, 0
	s_and_saveexec_b64 s[22:23], vcc
	s_cbranch_execz .LBB0_136
	v_or_b32_e32 v32, 28, v16
	v_ashrrev_i32_e32 v33, 31, v32
	v_lshlrev_b64 v[32:33], 12, v[32:33]
	v_lshl_add_u64 v[32:33], v[14:15], 0, v[32:33]
	global_load_dword v31, v[32:33], off nt
.LBB0_136:
	s_or_b64 exec, exec, s[22:23]
	s_and_saveexec_b64 s[22:23], vcc
	s_cbranch_execz .LBB0_138
	v_or_b32_e32 v32, 30, v16
	v_ashrrev_i32_e32 v33, 31, v32
	v_lshlrev_b64 v[32:33], 12, v[32:33]
	v_lshl_add_u64 v[32:33], v[14:15], 0, v[32:33]
	global_load_dword v30, v[32:33], off nt
; #define LAS __attribute__((address_space(3)))
; template <int MAP> __device__ __forceinline__ void transpose_item(const float* __restrict__ W, const float* __restrict__ gk, int K, int N, u16* __restrict__ WT, LAS float* scr, int item, int lane) {
;     const int nblk = (N + 31) >> 5, kb = item / nblk, nb = item - kb * nblk, k0 = 64 * kb, n0 = 32 * nb;
;     const int nn = n0 + (lane & 31); const bool ok = nn < N;
;     float wv[32];
; #pragma unroll
;     for (int i = 0; i < 32; ++i) { const int kk = 2 * i + (lane >> 5); wv[i] = ok ? W[(size_t)(k0 + kk) * N + nn] : 0.f; }
.LBB0_138:
	s_or_b64 exec, exec, s[22:23]
	v_mov_b32_e32 v32, 0
	v_mov_b32_e32 v33, 0
	s_and_saveexec_b64 s[22:23], vcc
	s_cbranch_execz .LBB0_140
	v_or_b32_e32 v56, 32, v16
	v_ashrrev_i32_e32 v57, 31, v56
	v_lshlrev_b64 v[56:57], 12, v[56:57]
	v_lshl_add_u64 v[56:57], v[14:15], 0, v[56:57]
	global_load_dword v33, v[56:57], off nt
.LBB0_140:
	s_or_b64 exec, exec, s[22:23]
	s_and_saveexec_b64 s[22:23], vcc
	s_cbranch_execz .LBB0_142
	v_or_b32_e32 v56, 34, v16
	v_ashrrev_i32_e32 v57, 31, v56
	v_lshlrev_b64 v[56:57], 12, v[56:57]
	v_lshl_add_u64 v[56:57], v[14:15], 0, v[56:57]
	global_load_dword v32, v[56:57], off nt
.LBB0_142:
	s_or_b64 exec, exec, s[22:23]
	v_mov_b32_e32 v56, 0
	v_mov_b32_e32 v57, 0
	s_and_saveexec_b64 s[22:23], vcc
	s_cbranch_execz .LBB0_144
	v_or_b32_e32 v58, 36, v16
	v_ashrrev_i32_e32 v59, 31, v58
	v_lshlrev_b64 v[58:59], 12, v[58:59]
	v_lshl_add_u64 v[58:59], v[14:15], 0, v[58:59]
	global_load_dword v57, v[58:59], off nt
.LBB0_144:
	s_or_b64 exec, exec, s[22:23]
	s_and_saveexec_b64 s[22:23], vcc
	s_cbranch_execz .LBB0_146
	v_or_b32_e32 v58, 38, v16
	v_ashrrev_i32_e32 v59, 31, v58
	v_lshlrev_b64 v[58:59], 12, v[58:59]
	v_lshl_add_u64 v[58:59], v[14:15], 0, v[58:59]
	global_load_dword v56, v[58:59], off nt
.LBB0_146:
	s_or_b64 exec, exec, s[22:23]
	v_mov_b32_e32 v58, 0
	v_mov_b32_e32 v59, 0
	s_and_saveexec_b64 s[22:23], vcc
	s_cbranch_execz .LBB0_148
	v_or_b32_e32 v60, 40, v16
	v_ashrrev_i32_e32 v61, 31, v60
	v_lshlrev_b64 v[60:61], 12, v[60:61]
	v_lshl_add_u64 v[60:61], v[14:15], 0, v[60:61]
	global_load_dword v59, v[60:61], off nt
.LBB0_148:
	s_or_b64 exec, exec, s[22:23]
	s_and_saveexec_b64 s[22:23], vcc
	s_cbranch_execz .LBB0_150
	v_or_b32_e32 v60, 42, v16
	v_ashrrev_i32_e32 v61, 31, v60
	v_lshlrev_b64 v[60:61], 12, v[60:61]
	v_lshl_add_u64 v[60:61], v[14:15], 0, v[60:61]
	global_load_dword v58, v[60:61], off nt
.LBB0_150:
	s_or_b64 exec, exec, s[22:23]
	v_mov_b32_e32 v60, 0
	v_mov_b32_e32 v61, 0
	s_and_saveexec_b64 s[22:23], vcc
	s_cbranch_execz .LBB0_152
	v_or_b32_e32 v62, 44, v16
	v_ashrrev_i32_e32 v63, 31, v62
	v_lshlrev_b64 v[62:63], 12, v[62:63]
	v_lshl_add_u64 v[62:63], v[14:15], 0, v[62:63]
	global_load_dword v61, v[62:63], off nt
.LBB0_152:
	s_or_b64 exec, exec, s[22:23]
	s_and_saveexec_b64 s[22:23], vcc
	s_cbranch_execz .LBB0_154
	v_or_b32_e32 v62, 46, v16
	v_ashrrev_i32_e32 v63, 31, v62
	v_lshlrev_b64 v[62:63], 12, v[62:63]
	v_lshl_add_u64 v[62:63], v[14:15], 0, v[62:63]
	global_load_dword v60, v[62:63], off nt
.LBB0_154:
	s_or_b64 exec, exec, s[22:23]
	v_mov_b32_e32 v62, 0
	v_mov_b32_e32 v63, 0
	s_and_saveexec_b64 s[22:23], vcc
	s_cbranch_execz .LBB0_156
	v_or_b32_e32 v64, 48, v16
	v_ashrrev_i32_e32 v65, 31, v64
	v_lshlrev_b64 v[64:65], 12, v[64:65]
	v_lshl_add_u64 v[64:65], v[14:15], 0, v[64:65]
	global_load_dword v63, v[64:65], off nt
.LBB0_156:
	s_or_b64 exec, exec, s[22:23]
	s_and_saveexec_b64 s[22:23], vcc
	s_cbranch_execz .LBB0_158
	v_or_b32_e32 v64, 50, v16
	v_ashrrev_i32_e32 v65, 31, v64
	v_lshlrev_b64 v[64:65], 12, v[64:65]
	v_lshl_add_u64 v[64:65], v[14:15], 0, v[64:65]
	global_load_dword v62, v[64:65], off nt
.LBB0_158:
	s_or_b64 exec, exec, s[22:23]
	v_mov_b32_e32 v64, 0
	v_mov_b32_e32 v65, 0
	s_and_saveexec_b64 s[22:23], vcc
	s_cbranch_execz .LBB0_160
	v_or_b32_e32 v66, 52, v16
	v_ashrrev_i32_e32 v67, 31, v66
	v_lshlrev_b64 v[66:67], 12, v[66:67]
	v_lshl_add_u64 v[66:67], v[14:15], 0, v[66:67]
	global_load_dword v65, v[66:67], off nt
.LBB0_160:
	s_or_b64 exec, exec, s[22:23]
	s_and_saveexec_b64 s[22:23], vcc
	s_cbranch_execz .LBB0_162
	v_or_b32_e32 v66, 54, v16
	v_ashrrev_i32_e32 v67, 31, v66
	v_lshlrev_b64 v[66:67], 12, v[66:67]
	v_lshl_add_u64 v[66:67], v[14:15], 0, v[66:67]
	global_load_dword v64, v[66:67], off nt
.LBB0_162:
	s_or_b64 exec, exec, s[22:23]
	v_mov_b32_e32 v66, 0
	v_mov_b32_e32 v67, 0
	s_and_saveexec_b64 s[22:23], vcc
	s_cbranch_execz .LBB0_164
	v_or_b32_e32 v68, 56, v16
	v_ashrrev_i32_e32 v69, 31, v68
	v_lshlrev_b64 v[68:69], 12, v[68:69]
	v_lshl_add_u64 v[68:69], v[14:15], 0, v[68:69]
	global_load_dword v67, v[68:69], off nt
.LBB0_164:
	s_or_b64 exec, exec, s[22:23]
	s_and_saveexec_b64 s[22:23], vcc
	s_cbranch_execz .LBB0_166
	v_or_b32_e32 v68, 58, v16
	v_ashrrev_i32_e32 v69, 31, v68
	v_lshlrev_b64 v[68:69], 12, v[68:69]
	v_lshl_add_u64 v[68:69], v[14:15], 0, v[68:69]
	global_load_dword v66, v[68:69], off nt
.LBB0_166:
	s_or_b64 exec, exec, s[22:23]
	v_mov_b32_e32 v68, 0
	v_mov_b32_e32 v69, 0
	s_and_saveexec_b64 s[22:23], vcc
	s_cbranch_execz .LBB0_168
	v_or_b32_e32 v70, 60, v16
	v_ashrrev_i32_e32 v71, 31, v70
	v_lshlrev_b64 v[70:71], 12, v[70:71]
	v_lshl_add_u64 v[70:71], v[14:15], 0, v[70:71]
	global_load_dword v69, v[70:71], off nt
.LBB0_168:
	s_or_b64 exec, exec, s[22:23]
	s_and_saveexec_b64 s[22:23], vcc
	s_cbranch_execz .LBB0_170
	v_or_b32_e32 v70, 62, v16
	v_ashrrev_i32_e32 v71, 31, v70
	v_lshlrev_b64 v[70:71], 12, v[70:71]
	v_lshl_add_u64 v[14:15], v[14:15], 0, v[70:71]
	global_load_dword v68, v[14:15], off nt

; #define LAS __attribute__((address_space(3)))
; template <int MAP> __device__ __forceinline__ void transpose_item(const float* __restrict__ W, const float* __restrict__ gk, int K, int N, u16* __restrict__ WT, LAS float* scr, int item, int lane) {
;     const int nblk = (N + 31) >> 5, kb = item / nblk, nb = item - kb * nblk, k0 = 64 * kb, n0 = 32 * nb;
;     const int nn = n0 + (lane & 31); const bool ok = nn < N;
;     float wv[32];
; #pragma unroll
;     for (int i = 0; i < 32; ++i) { const int kk = 2 * i + (lane >> 5); wv[i] = ok ? W[(size_t)(k0 + kk) * N + nn] : 0.f; }
.LBB0_183:
	s_mul_hi_i32 s0, s93, 0xb11fd3b9
	s_add_i32 s0, s0, s93
	s_lshr_b32 s1, s0, 31
	s_ashr_i32 s0, s0, 7
	s_add_i32 s62, s0, s1
	s_mul_i32 s68, s62, 0xffffe8e0
	s_add_i32 s68, s68, s94
	v_add_u32_e32 v14, s68, v34
	s_lshl_b32 s64, s62, 6
	v_ashrrev_i32_e32 v15, 31, v14
	v_cmp_gt_i32_e32 vcc, s84, v14
	v_or_b32_e32 v16, s64, v6
	v_lshl_add_u64 v[22:23], v[14:15], 2, s[60:61]
	v_mov_b32_e32 v8, 0
	v_mov_b32_e32 v57, 0
	s_and_saveexec_b64 s[0:1], vcc
	s_cbranch_execz .LBB0_185
	v_mad_i64_i32 v[14:15], s[22:23], v16, s85, v[22:23]
	global_load_dword v57, v[14:15], off nt
.LBB0_185:
	s_or_b64 exec, exec, s[0:1]
	s_and_saveexec_b64 s[0:1], vcc
	s_cbranch_execz .LBB0_187
	v_or_b32_e32 v8, 2, v16
	v_mad_i64_i32 v[14:15], s[22:23], v8, s85, v[22:23]
	global_load_dword v8, v[14:15], off nt
.LBB0_187:
	s_or_b64 exec, exec, s[0:1]
	v_mov_b32_e32 v60, 0
	v_mov_b32_e32 v61, 0
	s_and_saveexec_b64 s[0:1], vcc
	s_cbranch_execz .LBB0_189
	v_or_b32_e32 v14, 4, v16
	v_mad_i64_i32 v[14:15], s[22:23], v14, s85, v[22:23]
	global_load_dword v61, v[14:15], off nt
.LBB0_189:
	s_or_b64 exec, exec, s[0:1]
	s_and_saveexec_b64 s[0:1], vcc
	s_cbranch_execz .LBB0_191
	v_or_b32_e32 v14, 6, v16
	v_mad_i64_i32 v[14:15], s[22:23], v14, s85, v[22:23]
	global_load_dword v60, v[14:15], off nt
.LBB0_191:
	s_or_b64 exec, exec, s[0:1]
	v_mov_b32_e32 v15, 0
	v_mov_b32_e32 v14, 0
	s_and_saveexec_b64 s[0:1], vcc
	s_cbranch_execz .LBB0_193
	v_or_b32_e32 v14, 8, v16
	v_mad_i64_i32 v[18:19], s[22:23], v14, s85, v[22:23]
	global_load_dword v14, v[18:19], off nt
.LBB0_193:
	s_or_b64 exec, exec, s[0:1]
	s_and_saveexec_b64 s[0:1], vcc
	s_cbranch_execz .LBB0_195
	v_or_b32_e32 v15, 10, v16
	v_mad_i64_i32 v[18:19], s[22:23], v15, s85, v[22:23]
	global_load_dword v15, v[18:19], off nt
.LBB0_195:
	s_or_b64 exec, exec, s[0:1]
	v_mov_b32_e32 v21, 0
	v_mov_b32_e32 v20, 0
	s_and_saveexec_b64 s[0:1], vcc
	s_cbranch_execz .LBB0_197
	v_or_b32_e32 v17, 12, v16
	v_mad_i64_i32 v[18:19], s[22:23], v17, s85, v[22:23]
	global_load_dword v20, v[18:19], off nt
.LBB0_197:
	s_or_b64 exec, exec, s[0:1]
	s_and_saveexec_b64 s[0:1], vcc
	s_cbranch_execz .LBB0_199
	v_or_b32_e32 v17, 14, v16
	v_mad_i64_i32 v[18:19], s[22:23], v17, s85, v[22:23]
	global_load_dword v21, v[18:19], off nt
.LBB0_199:
	s_or_b64 exec, exec, s[0:1]
	v_mov_b32_e32 v58, 0
	v_mov_b32_e32 v59, 0
	s_and_saveexec_b64 s[0:1], vcc
	s_cbranch_execz .LBB0_201
	v_or_b32_e32 v17, 16, v16
	v_mad_i64_i32 v[18:19], s[22:23], v17, s85, v[22:23]
	global_load_dword v59, v[18:19], off nt
.LBB0_201:
	s_or_b64 exec, exec, s[0:1]
	s_and_saveexec_b64 s[0:1], vcc
	s_cbranch_execz .LBB0_203
	v_or_b32_e32 v17, 18, v16
	v_mad_i64_i32 v[18:19], s[22:23], v17, s85, v[22:23]
	global_load_dword v58, v[18:19], off nt
.LBB0_203:
	s_or_b64 exec, exec, s[0:1]
	v_mov_b32_e32 v64, 0
	v_mov_b32_e32 v65, 0
	s_and_saveexec_b64 s[0:1], vcc
	s_cbranch_execz .LBB0_205
	v_or_b32_e32 v17, 20, v16
	v_mad_i64_i32 v[18:19], s[22:23], v17, s85, v[22:23]
	global_load_dword v65, v[18:19], off nt
.LBB0_205:
	s_or_b64 exec, exec, s[0:1]
	s_and_saveexec_b64 s[0:1], vcc
	s_cbranch_execz .LBB0_207
	v_or_b32_e32 v17, 22, v16
	v_mad_i64_i32 v[18:19], s[22:23], v17, s85, v[22:23]
	global_load_dword v64, v[18:19], off nt
.LBB0_207:
	s_or_b64 exec, exec, s[0:1]
	v_mov_b32_e32 v19, 0
	v_mov_b32_e32 v18, 0
	s_and_saveexec_b64 s[0:1], vcc
	s_cbranch_execz .LBB0_209
	v_or_b32_e32 v17, 24, v16
	v_mad_i64_i32 v[24:25], s[22:23], v17, s85, v[22:23]
	global_load_dword v18, v[24:25], off nt
.LBB0_209:
	s_or_b64 exec, exec, s[0:1]
	s_and_saveexec_b64 s[0:1], vcc
	s_cbranch_execz .LBB0_211
	v_or_b32_e32 v17, 26, v16
	v_mad_i64_i32 v[24:25], s[22:23], v17, s85, v[22:23]
	global_load_dword v19, v[24:25], off nt
.LBB0_211:
	s_or_b64 exec, exec, s[0:1]
	v_mov_b32_e32 v27, 0
	v_mov_b32_e32 v26, 0
	s_and_saveexec_b64 s[0:1], vcc
	s_cbranch_execz .LBB0_213
	v_or_b32_e32 v17, 28, v16
	v_mad_i64_i32 v[24:25], s[22:23], v17, s85, v[22:23]
	global_load_dword v26, v[24:25], off nt
.LBB0_213:
	s_or_b64 exec, exec, s[0:1]
	s_and_saveexec_b64 s[0:1], vcc
	s_cbranch_execz .LBB0_215
	v_or_b32_e32 v17, 30, v16
	v_mad_i64_i32 v[24:25], s[22:23], v17, s85, v[22:23]
	global_load_dword v27, v[24:25], off nt
.LBB0_215:
	s_or_b64 exec, exec, s[0:1]
	v_mov_b32_e32 v62, 0
	v_mov_b32_e32 v63, 0
	s_and_saveexec_b64 s[0:1], vcc
	s_cbranch_execz .LBB0_217
	v_or_b32_e32 v17, 32, v16
	v_mad_i64_i32 v[24:25], s[22:23], v17, s85, v[22:23]
	global_load_dword v63, v[24:25], off nt
.LBB0_217:
	s_or_b64 exec, exec, s[0:1]
	s_and_saveexec_b64 s[0:1], vcc
	s_cbranch_execz .LBB0_219
	v_or_b32_e32 v17, 34, v16
	v_mad_i64_i32 v[24:25], s[22:23], v17, s85, v[22:23]
	global_load_dword v62, v[24:25], off nt
; #define LAS __attribute__((address_space(3)))
; template <int MAP> __device__ __forceinline__ void transpose_item(const float* __restrict__ W, const float* __restrict__ gk, int K, int N, u16* __restrict__ WT, LAS float* scr, int item, int lane) {
;     const int nblk = (N + 31) >> 5, kb = item / nblk, nb = item - kb * nblk, k0 = 64 * kb, n0 = 32 * nb;
;     const int nn = n0 + (lane & 31); const bool ok = nn < N;
;     float wv[32];
; #pragma unroll
;     for (int i = 0; i < 32; ++i) { const int kk = 2 * i + (lane >> 5); wv[i] = ok ? W[(size_t)(k0 + kk) * N + nn] : 0.f; }
; #pragma unroll
;     for (int i = 0; i < 32; ++i) { const int kk = 2 * i + (lane >> 5); float w = wv[i]; if (gk) w *= gk[k0 + kk]; scr[kk * 33 + (lane & 31)] = w; }
.LBB0_219:
	s_or_b64 exec, exec, s[0:1]
	v_mov_b32_e32 v68, 0
	v_mov_b32_e32 v69, 0
	s_and_saveexec_b64 s[0:1], vcc
	s_cbranch_execz .LBB0_221
	v_or_b32_e32 v17, 36, v16
	v_mad_i64_i32 v[24:25], s[22:23], v17, s85, v[22:23]
	global_load_dword v69, v[24:25], off nt
.LBB0_221:
	s_or_b64 exec, exec, s[0:1]
	s_and_saveexec_b64 s[0:1], vcc
	s_cbranch_execz .LBB0_223
	v_or_b32_e32 v17, 38, v16
	v_mad_i64_i32 v[24:25], s[22:23], v17, s85, v[22:23]
	global_load_dword v68, v[24:25], off nt
.LBB0_223:
	s_or_b64 exec, exec, s[0:1]
	v_mov_b32_e32 v25, 0
	v_mov_b32_e32 v24, 0
	s_and_saveexec_b64 s[0:1], vcc
	s_cbranch_execz .LBB0_225
	v_or_b32_e32 v17, 40, v16
	v_mad_i64_i32 v[28:29], s[22:23], v17, s85, v[22:23]
	global_load_dword v24, v[28:29], off nt
.LBB0_225:
	s_or_b64 exec, exec, s[0:1]
	s_and_saveexec_b64 s[0:1], vcc
	s_cbranch_execz .LBB0_227
	v_or_b32_e32 v17, 42, v16
	v_mad_i64_i32 v[28:29], s[22:23], v17, s85, v[22:23]
	global_load_dword v25, v[28:29], off nt
.LBB0_227:
	s_or_b64 exec, exec, s[0:1]
	v_mov_b32_e32 v31, 0
	v_mov_b32_e32 v30, 0
	s_and_saveexec_b64 s[0:1], vcc
	s_cbranch_execz .LBB0_229
	v_or_b32_e32 v17, 44, v16
	v_mad_i64_i32 v[28:29], s[22:23], v17, s85, v[22:23]
	global_load_dword v30, v[28:29], off nt
.LBB0_229:
	s_or_b64 exec, exec, s[0:1]
	s_and_saveexec_b64 s[0:1], vcc
	s_cbranch_execz .LBB0_231
	v_or_b32_e32 v17, 46, v16
	v_mad_i64_i32 v[28:29], s[22:23], v17, s85, v[22:23]
	global_load_dword v31, v[28:29], off nt
.LBB0_231:
	s_or_b64 exec, exec, s[0:1]
	v_mov_b32_e32 v66, 0
	v_mov_b32_e32 v67, 0
	s_and_saveexec_b64 s[0:1], vcc
	s_cbranch_execz .LBB0_233
	v_or_b32_e32 v17, 48, v16
	v_mad_i64_i32 v[28:29], s[22:23], v17, s85, v[22:23]
	global_load_dword v67, v[28:29], off nt
.LBB0_233:
	s_or_b64 exec, exec, s[0:1]
	s_and_saveexec_b64 s[0:1], vcc
	s_cbranch_execz .LBB0_235
	v_or_b32_e32 v17, 50, v16
	v_mad_i64_i32 v[28:29], s[22:23], v17, s85, v[22:23]
	global_load_dword v66, v[28:29], off nt
.LBB0_235:
	s_or_b64 exec, exec, s[0:1]
	v_mov_b32_e32 v70, 0
	v_mov_b32_e32 v71, 0
	s_and_saveexec_b64 s[0:1], vcc
	s_cbranch_execz .LBB0_237
	v_or_b32_e32 v17, 52, v16
	v_mad_i64_i32 v[28:29], s[22:23], v17, s85, v[22:23]
	global_load_dword v71, v[28:29], off nt
.LBB0_237:
	s_or_b64 exec, exec, s[0:1]
	s_and_saveexec_b64 s[0:1], vcc
	s_cbranch_execz .LBB0_239
	v_or_b32_e32 v17, 54, v16
	v_mad_i64_i32 v[28:29], s[22:23], v17, s85, v[22:23]
	global_load_dword v70, v[28:29], off nt
.LBB0_239:
	s_or_b64 exec, exec, s[0:1]
	v_mov_b32_e32 v29, 0
	v_mov_b32_e32 v28, 0
	s_and_saveexec_b64 s[0:1], vcc
	s_cbranch_execz .LBB0_241
	v_or_b32_e32 v17, 56, v16
	v_mad_i64_i32 v[32:33], s[22:23], v17, s85, v[22:23]
	global_load_dword v28, v[32:33], off nt
.LBB0_241:
	s_or_b64 exec, exec, s[0:1]
	s_and_saveexec_b64 s[0:1], vcc
	s_cbranch_execz .LBB0_243
	v_or_b32_e32 v17, 58, v16
	v_mad_i64_i32 v[32:33], s[22:23], v17, s85, v[22:23]
	global_load_dword v29, v[32:33], off nt
.LBB0_243:
	s_or_b64 exec, exec, s[0:1]
	v_mov_b32_e32 v33, 0
	v_mov_b32_e32 v32, 0
	s_and_saveexec_b64 s[0:1], vcc
	s_cbranch_execz .LBB0_245
	v_or_b32_e32 v17, 60, v16
	v_mad_i64_i32 v[72:73], s[22:23], v17, s85, v[22:23]
	global_load_dword v32, v[72:73], off nt
.LBB0_245:
	s_or_b64 exec, exec, s[0:1]
	s_and_saveexec_b64 s[0:1], vcc
	s_cbranch_execz .LBB0_247
	v_or_b32_e32 v17, 62, v16
	v_mad_i64_i32 v[22:23], s[22:23], v17, s85, v[22:23]
	global_load_dword v33, v[22:23], off nt
.LBB0_247:
	s_or_b64 exec, exec, s[0:1]
	v_cndmask_b32_e64 v17, 0, 1, s[50:51]
	v_cmp_ne_u32_e64 s[0:1], 1, v17
	s_andn2_b64 vcc, exec, s[50:51]
	s_cbranch_vccnz .LBB0_298
	v_ashrrev_i32_e32 v17, 31, v16
	s_ashr_i32 s65, s64, 31
	v_lshl_add_u64 v[16:17], v[16:17], 2, s[58:59]
	v_lshl_add_u64 v[22:23], s[64:65], 0, v[6:7]
	v_lshl_add_u64 v[22:23], v[22:23], 2, s[58:59]
	global_load_dword v78, v[16:17], off nt
	global_load_dword v79, v[22:23], off offset:8 nt
	global_load_dword v80, v[22:23], off offset:16 nt
	global_load_dword v81, v[22:23], off offset:24 nt
	s_nop 0
	global_load_dword v16, v[22:23], off offset:32 nt
	global_load_dword v17, v[22:23], off offset:40 nt
	global_load_dword v72, v[22:23], off offset:48 nt
	global_load_dword v73, v[22:23], off offset:56 nt
	v_add_u32_e32 v82, v35, v37
	s_waitcnt vmcnt(7)
	v_mul_f32_e32 v22, v57, v78
	s_waitcnt vmcnt(6)
	v_mul_f32_e32 v78, v8, v79
	s_waitcnt vmcnt(5)
	v_mul_f32_e32 v79, v61, v80
	ds_write_b32 v36, v22
	s_waitcnt vmcnt(4)
	v_mul_f32_e32 v80, v60, v81
	s_waitcnt vmcnt(2)
	v_pk_mul_f32 v[16:17], v[14:15], v[16:17]
	ds_write2_b32 v82, v78, v79 offset1:66
	ds_write_b32 v82, v80 offset:528
	s_waitcnt vmcnt(0)
	v_pk_mul_f32 v[22:23], v[20:21], v[72:73]
	s_cbranch_execnz .LBB0_250

; template <int MAP> __device__ __forceinline__ void transpose_item(const float* __restrict__ W, const float* __restrict__ gk, int K, int N, u16* __restrict__ WT, LAS float* scr, int item, int lane) {
;     ...
; #pragma unroll
;     for (int i = 0; i < 32; ++i) { const int kk = 2 * i + (lane >> 5); float w = wv[i]; if (gk) w *= gk[k0 + kk]; scr[kk * 33 + (lane & 31)] = w; }
.LBB0_250:
	s_waitcnt vmcnt(0)
	v_add_u32_e32 v8, v35, v38
	s_and_b64 vcc, exec, s[0:1]
	ds_write2_b32 v8, v16, v17 offset1:66
	ds_write2_b32 v8, v22, v23 offset0:132 offset1:198
	s_cbranch_vccnz .LBB0_299
	s_ashr_i32 s65, s64, 31
	v_lshl_add_u64 v[14:15], s[64:65], 0, v[6:7]
	v_lshl_add_u64 v[14:15], v[14:15], 2, s[58:59]
	global_load_dword v8, v[14:15], off offset:64 nt
	global_load_dword v22, v[14:15], off offset:72 nt
	global_load_dword v23, v[14:15], off offset:80 nt
	global_load_dword v57, v[14:15], off offset:88 nt
	global_load_dword v16, v[14:15], off offset:96 nt
	global_load_dword v17, v[14:15], off offset:104 nt
	global_load_dword v20, v[14:15], off offset:112 nt
	global_load_dword v21, v[14:15], off offset:120 nt
	v_add_u32_e32 v60, v35, v39
	s_waitcnt vmcnt(7)
	v_mul_f32_e32 v8, v59, v8
	s_waitcnt vmcnt(6)
	v_mul_f32_e32 v22, v58, v22
	s_waitcnt vmcnt(5)
	v_mul_f32_e32 v23, v65, v23
	s_waitcnt vmcnt(4)
	v_mul_f32_e32 v57, v64, v57
	ds_write2_b32 v60, v8, v22 offset1:66
	ds_write2_b32 v60, v23, v57 offset0:132 offset1:198
	s_waitcnt vmcnt(2)
	v_pk_mul_f32 v[14:15], v[18:19], v[16:17]
	s_waitcnt vmcnt(0)
	v_pk_mul_f32 v[16:17], v[26:27], v[20:21]
	s_cbranch_execnz .LBB0_253

; template <int MAP> __device__ __forceinline__ void transpose_item(const float* __restrict__ W, const float* __restrict__ gk, int K, int N, u16* __restrict__ WT, LAS float* scr, int item, int lane) {
;     ...
; #pragma unroll
;     for (int i = 0; i < 32; ++i) { const int kk = 2 * i + (lane >> 5); float w = wv[i]; if (gk) w *= gk[k0 + kk]; scr[kk * 33 + (lane & 31)] = w; }
.LBB0_253:
	v_add_u32_e32 v8, v35, v40
	s_and_b64 vcc, exec, s[0:1]
	ds_write2_b32 v8, v14, v15 offset1:66
	ds_write2_b32 v8, v16, v17 offset0:132 offset1:198
	s_cbranch_vccnz .LBB0_300
	s_ashr_i32 s65, s64, 31
	v_lshl_add_u64 v[14:15], s[64:65], 0, v[6:7]
	v_lshl_add_u64 v[14:15], v[14:15], 2, s[58:59]
	global_load_dword v8, v[14:15], off offset:128 nt
	global_load_dword v20, v[14:15], off offset:136 nt
	global_load_dword v21, v[14:15], off offset:144 nt
	global_load_dword v22, v[14:15], off offset:152 nt
	global_load_dword v16, v[14:15], off offset:160 nt
	global_load_dword v17, v[14:15], off offset:168 nt
	global_load_dword v18, v[14:15], off offset:176 nt
	global_load_dword v19, v[14:15], off offset:184 nt
	v_add_u32_e32 v23, v35, v41
	s_waitcnt vmcnt(7)
	v_mul_f32_e32 v8, v63, v8
	s_waitcnt vmcnt(6)
	v_mul_f32_e32 v20, v62, v20
	s_waitcnt vmcnt(5)
	v_mul_f32_e32 v21, v69, v21
	s_waitcnt vmcnt(4)
	v_mul_f32_e32 v22, v68, v22
	ds_write2_b32 v23, v8, v20 offset1:66
	ds_write2_b32 v23, v21, v22 offset0:132 offset1:198
	s_waitcnt vmcnt(2)
	v_pk_mul_f32 v[14:15], v[24:25], v[16:17]
	s_waitcnt vmcnt(0)
	v_pk_mul_f32 v[16:17], v[30:31], v[18:19]
	s_cbranch_execnz .LBB0_256

; template <int MAP> __device__ __forceinline__ void transpose_item(const float* __restrict__ W, const float* __restrict__ gk, int K, int N, u16* __restrict__ WT, LAS float* scr, int item, int lane) {
;     ...
; #pragma unroll
;     for (int i = 0; i < 32; ++i) { const int kk = 2 * i + (lane >> 5); float w = wv[i]; if (gk) w *= gk[k0 + kk]; scr[kk * 33 + (lane & 31)] = w; }
.LBB0_256:
	v_add_u32_e32 v8, v35, v42
	s_and_b64 vcc, exec, s[0:1]
	ds_write2_b32 v8, v14, v15 offset1:66
	ds_write2_b32 v8, v16, v17 offset0:132 offset1:198
	s_cbranch_vccnz .LBB0_301
	s_ashr_i32 s65, s64, 31
	v_lshl_add_u64 v[14:15], s[64:65], 0, v[6:7]
	v_lshl_add_u64 v[14:15], v[14:15], 2, s[58:59]
	global_load_dword v8, v[14:15], off offset:192 nt
	global_load_dword v20, v[14:15], off offset:200 nt
	global_load_dword v21, v[14:15], off offset:208 nt
	global_load_dword v22, v[14:15], off offset:216 nt
	global_load_dword v16, v[14:15], off offset:224 nt
	global_load_dword v17, v[14:15], off offset:232 nt
	global_load_dword v18, v[14:15], off offset:240 nt
	global_load_dword v19, v[14:15], off offset:248 nt
	v_add_u32_e32 v23, v35, v43
	s_waitcnt vmcnt(7)
	v_mul_f32_e32 v8, v67, v8
	s_waitcnt vmcnt(6)
	v_mul_f32_e32 v20, v66, v20
	s_waitcnt vmcnt(5)
	v_mul_f32_e32 v21, v71, v21
	s_waitcnt vmcnt(4)
	v_mul_f32_e32 v22, v70, v22
	ds_write2_b32 v23, v8, v20 offset1:66
	ds_write2_b32 v23, v21, v22 offset0:132 offset1:198
	s_waitcnt vmcnt(2)
	v_pk_mul_f32 v[14:15], v[28:29], v[16:17]
	s_waitcnt vmcnt(0)
	v_pk_mul_f32 v[16:17], v[32:33], v[18:19]
	s_cbranch_execnz .LBB0_259

; #define LAS __attribute__((address_space(3)))
; template <int MAP> __device__ __forceinline__ void transpose_item(const float* __restrict__ W, const float* __restrict__ gk, int K, int N, u16* __restrict__ WT, LAS float* scr, int item, int lane) {
;     const int nblk = (N + 31) >> 5, kb = item / nblk, nb = item - kb * nblk, k0 = 64 * kb, n0 = 32 * nb;
;     const int nn = n0 + (lane & 31); const bool ok = nn < N;
;     float wv[32];
; #pragma unroll
;     for (int i = 0; i < 32; ++i) { const int kk = 2 * i + (lane >> 5); wv[i] = ok ? W[(size_t)(k0 + kk) * N + nn] : 0.f; }
.LBB0_605:
	s_ashr_i32 s22, s61, 31
	s_lshr_b32 s22, s22, 27
	s_add_i32 s22, s61, s22
	s_ashr_i32 s58, s22, 5
	s_lshl_b32 s59, s58, 10
	s_sub_i32 s22, s62, s59
	v_add_u32_e32 v14, s22, v34
	v_ashrrev_i32_e32 v15, 31, v14
	v_cmp_gt_i32_e32 vcc, s79, v14
	v_lshl_or_b32 v16, s58, 6, v6
	v_lshl_add_u64 v[14:15], v[14:15], 2, s[0:1]
	v_mov_b32_e32 v18, 0
	v_mov_b32_e32 v8, 0
	s_and_saveexec_b64 s[22:23], vcc
	s_cbranch_execz .LBB0_607
	v_ashrrev_i32_e32 v17, 31, v16
	v_lshlrev_b64 v[20:21], 12, v[16:17]
	v_lshl_add_u64 v[20:21], v[14:15], 0, v[20:21]
	global_load_dword v8, v[20:21], off nt

; #define LAS __attribute__((address_space(3)))
; template <int MAP> __device__ __forceinline__ void transpose_item(const float* __restrict__ W, const float* __restrict__ gk, int K, int N, u16* __restrict__ WT, LAS float* scr, int item, int lane) {
;     const int nblk = (N + 31) >> 5, kb = item / nblk, nb = item - kb * nblk, k0 = 64 * kb, n0 = 32 * nb;
;     const int nn = n0 + (lane & 31); const bool ok = nn < N;
;     float wv[32];
; #pragma unroll
;     for (int i = 0; i < 32; ++i) { const int kk = 2 * i + (lane >> 5); wv[i] = ok ? W[(size_t)(k0 + kk) * N + nn] : 0.f; }
.LBB0_680:
	s_mul_hi_i32 s0, s23, 0x2e8ba2e9
	s_lshr_b32 s1, s0, 31
	s_ashr_i32 s0, s0, 5
	s_add_i32 s60, s0, s1
	s_mul_i32 s66, s60, 0xffffea00
	s_add_i32 s0, s66, s34
	v_add_u32_e32 v14, s0, v57
	s_lshl_b32 s62, s60, 6
	v_ashrrev_i32_e32 v15, 31, v14
	v_cmp_gt_i32_e32 vcc, s73, v14
	v_or_b32_e32 v16, s62, v6
	v_lshl_add_u64 v[22:23], v[14:15], 2, s[58:59]
	v_mov_b32_e32 v8, 0
	v_mov_b32_e32 v58, 0
	s_and_saveexec_b64 s[0:1], vcc
	s_cbranch_execz .LBB0_682
	v_mad_i64_i32 v[14:15], s[64:65], v16, s74, v[22:23]
	global_load_dword v58, v[14:15], off nt
.LBB0_682:
	s_or_b64 exec, exec, s[0:1]
	s_and_saveexec_b64 s[0:1], vcc
	s_cbranch_execz .LBB0_684
	v_or_b32_e32 v8, 2, v16
	v_mad_i64_i32 v[14:15], s[64:65], v8, s74, v[22:23]
	global_load_dword v8, v[14:15], off nt
.LBB0_684:
	s_or_b64 exec, exec, s[0:1]
	v_mov_b32_e32 v59, 0
	v_mov_b32_e32 v62, 0
	s_and_saveexec_b64 s[0:1], vcc
	s_cbranch_execz .LBB0_686
	v_or_b32_e32 v14, 4, v16
	v_mad_i64_i32 v[14:15], s[64:65], v14, s74, v[22:23]
	global_load_dword v62, v[14:15], off nt
.LBB0_686:
	s_or_b64 exec, exec, s[0:1]
	s_and_saveexec_b64 s[0:1], vcc
	s_cbranch_execz .LBB0_688
	v_or_b32_e32 v14, 6, v16
	v_mad_i64_i32 v[14:15], s[64:65], v14, s74, v[22:23]
	global_load_dword v59, v[14:15], off nt
.LBB0_688:
	s_or_b64 exec, exec, s[0:1]
	v_mov_b32_e32 v15, 0
	v_mov_b32_e32 v14, 0
	s_and_saveexec_b64 s[0:1], vcc
	s_cbranch_execz .LBB0_690
	v_or_b32_e32 v14, 8, v16
	v_mad_i64_i32 v[18:19], s[64:65], v14, s74, v[22:23]
	global_load_dword v14, v[18:19], off nt
.LBB0_690:
	s_or_b64 exec, exec, s[0:1]
	s_and_saveexec_b64 s[0:1], vcc
	s_cbranch_execz .LBB0_692
	v_or_b32_e32 v15, 10, v16
	v_mad_i64_i32 v[18:19], s[64:65], v15, s74, v[22:23]
	global_load_dword v15, v[18:19], off nt
.LBB0_692:
	s_or_b64 exec, exec, s[0:1]
	v_mov_b32_e32 v19, 0
	v_mov_b32_e32 v18, 0
	s_and_saveexec_b64 s[0:1], vcc
	s_cbranch_execz .LBB0_694
	v_or_b32_e32 v17, 12, v16
	v_mad_i64_i32 v[20:21], s[64:65], v17, s74, v[22:23]
	global_load_dword v18, v[20:21], off nt
.LBB0_694:
	s_or_b64 exec, exec, s[0:1]
	s_and_saveexec_b64 s[0:1], vcc
	s_cbranch_execz .LBB0_696
	v_or_b32_e32 v17, 14, v16
	v_mad_i64_i32 v[20:21], s[64:65], v17, s74, v[22:23]
	global_load_dword v19, v[20:21], off nt
.LBB0_696:
	s_or_b64 exec, exec, s[0:1]
	v_mov_b32_e32 v60, 0
	v_mov_b32_e32 v61, 0
	s_and_saveexec_b64 s[0:1], vcc
	s_cbranch_execz .LBB0_698
	v_or_b32_e32 v17, 16, v16
	v_mad_i64_i32 v[20:21], s[64:65], v17, s74, v[22:23]
	global_load_dword v61, v[20:21], off nt
.LBB0_698:
	s_or_b64 exec, exec, s[0:1]
	s_and_saveexec_b64 s[0:1], vcc
	s_cbranch_execz .LBB0_700
	v_or_b32_e32 v17, 18, v16
	v_mad_i64_i32 v[20:21], s[64:65], v17, s74, v[22:23]
	global_load_dword v60, v[20:21], off nt
.LBB0_700:
	s_or_b64 exec, exec, s[0:1]
	v_mov_b32_e32 v63, 0
	v_mov_b32_e32 v65, 0
	s_and_saveexec_b64 s[0:1], vcc
	s_cbranch_execz .LBB0_702
	v_or_b32_e32 v17, 20, v16
	v_mad_i64_i32 v[20:21], s[64:65], v17, s74, v[22:23]
	global_load_dword v65, v[20:21], off nt
.LBB0_702:
	s_or_b64 exec, exec, s[0:1]
	s_and_saveexec_b64 s[0:1], vcc
	s_cbranch_execz .LBB0_704
	v_or_b32_e32 v17, 22, v16
	v_mad_i64_i32 v[20:21], s[64:65], v17, s74, v[22:23]
	global_load_dword v63, v[20:21], off nt
.LBB0_704:
	s_or_b64 exec, exec, s[0:1]
	v_mov_b32_e32 v21, 0
	v_mov_b32_e32 v20, 0
	s_and_saveexec_b64 s[0:1], vcc
	s_cbranch_execz .LBB0_706
	v_or_b32_e32 v17, 24, v16
	v_mad_i64_i32 v[24:25], s[64:65], v17, s74, v[22:23]
	global_load_dword v20, v[24:25], off nt
.LBB0_706:
	s_or_b64 exec, exec, s[0:1]
	s_and_saveexec_b64 s[0:1], vcc
	s_cbranch_execz .LBB0_708
	v_or_b32_e32 v17, 26, v16
	v_mad_i64_i32 v[24:25], s[64:65], v17, s74, v[22:23]
	global_load_dword v21, v[24:25], off nt
.LBB0_708:
	s_or_b64 exec, exec, s[0:1]
	v_mov_b32_e32 v25, 0
	v_mov_b32_e32 v24, 0
	s_and_saveexec_b64 s[0:1], vcc
	s_cbranch_execz .LBB0_710
	v_or_b32_e32 v17, 28, v16
	v_mad_i64_i32 v[26:27], s[64:65], v17, s74, v[22:23]
	global_load_dword v24, v[26:27], off nt
.LBB0_710:
	s_or_b64 exec, exec, s[0:1]
	s_and_saveexec_b64 s[0:1], vcc
	s_cbranch_execz .LBB0_712
	v_or_b32_e32 v17, 30, v16
	v_mad_i64_i32 v[26:27], s[64:65], v17, s74, v[22:23]
	global_load_dword v25, v[26:27], off nt
.LBB0_712:
	s_or_b64 exec, exec, s[0:1]
	v_mov_b32_e32 v64, 0
	v_mov_b32_e32 v66, 0
	s_and_saveexec_b64 s[0:1], vcc
	s_cbranch_execz .LBB0_714
	v_or_b32_e32 v17, 32, v16
	v_mad_i64_i32 v[26:27], s[64:65], v17, s74, v[22:23]
	global_load_dword v66, v[26:27], off nt
.LBB0_714:
	s_or_b64 exec, exec, s[0:1]
	s_and_saveexec_b64 s[0:1], vcc
	s_cbranch_execz .LBB0_716
	v_or_b32_e32 v17, 34, v16
	v_mad_i64_i32 v[26:27], s[64:65], v17, s74, v[22:23]
	global_load_dword v64, v[26:27], off nt
; #define LAS __attribute__((address_space(3)))
; template <int MAP> __device__ __forceinline__ void transpose_item(const float* __restrict__ W, const float* __restrict__ gk, int K, int N, u16* __restrict__ WT, LAS float* scr, int item, int lane) {
;     const int nblk = (N + 31) >> 5, kb = item / nblk, nb = item - kb * nblk, k0 = 64 * kb, n0 = 32 * nb;
;     const int nn = n0 + (lane & 31); const bool ok = nn < N;
;     float wv[32];
; #pragma unroll
;     for (int i = 0; i < 32; ++i) { const int kk = 2 * i + (lane >> 5); wv[i] = ok ? W[(size_t)(k0 + kk) * N + nn] : 0.f; }
; #pragma unroll
;     for (int i = 0; i < 32; ++i) { const int kk = 2 * i + (lane >> 5); float w = wv[i]; if (gk) w *= gk[k0 + kk]; scr[kk * 33 + (lane & 31)] = w; }
.LBB0_716:
	s_or_b64 exec, exec, s[0:1]
	v_mov_b32_e32 v67, 0
	v_mov_b32_e32 v69, 0
	s_and_saveexec_b64 s[0:1], vcc
	s_cbranch_execz .LBB0_718
	v_or_b32_e32 v17, 36, v16
	v_mad_i64_i32 v[26:27], s[64:65], v17, s74, v[22:23]
	global_load_dword v69, v[26:27], off nt
.LBB0_718:
	s_or_b64 exec, exec, s[0:1]
	s_and_saveexec_b64 s[0:1], vcc
	s_cbranch_execz .LBB0_720
	v_or_b32_e32 v17, 38, v16
	v_mad_i64_i32 v[26:27], s[64:65], v17, s74, v[22:23]
	global_load_dword v67, v[26:27], off nt
.LBB0_720:
	s_or_b64 exec, exec, s[0:1]
	v_mov_b32_e32 v27, 0
	v_mov_b32_e32 v26, 0
	s_and_saveexec_b64 s[0:1], vcc
	s_cbranch_execz .LBB0_722
	v_or_b32_e32 v17, 40, v16
	v_mad_i64_i32 v[28:29], s[64:65], v17, s74, v[22:23]
	global_load_dword v26, v[28:29], off nt
.LBB0_722:
	s_or_b64 exec, exec, s[0:1]
	s_and_saveexec_b64 s[0:1], vcc
	s_cbranch_execz .LBB0_724
	v_or_b32_e32 v17, 42, v16
	v_mad_i64_i32 v[28:29], s[64:65], v17, s74, v[22:23]
	global_load_dword v27, v[28:29], off nt
.LBB0_724:
	s_or_b64 exec, exec, s[0:1]
	v_mov_b32_e32 v29, 0
	v_mov_b32_e32 v28, 0
	s_and_saveexec_b64 s[0:1], vcc
	s_cbranch_execz .LBB0_726
	v_or_b32_e32 v17, 44, v16
	v_mad_i64_i32 v[30:31], s[64:65], v17, s74, v[22:23]
	global_load_dword v28, v[30:31], off nt
.LBB0_726:
	s_or_b64 exec, exec, s[0:1]
	s_and_saveexec_b64 s[0:1], vcc
	s_cbranch_execz .LBB0_728
	v_or_b32_e32 v17, 46, v16
	v_mad_i64_i32 v[30:31], s[64:65], v17, s74, v[22:23]
	global_load_dword v29, v[30:31], off nt
.LBB0_728:
	s_or_b64 exec, exec, s[0:1]
	v_mov_b32_e32 v68, 0
	v_mov_b32_e32 v70, 0
	s_and_saveexec_b64 s[0:1], vcc
	s_cbranch_execz .LBB0_730
	v_or_b32_e32 v17, 48, v16
	v_mad_i64_i32 v[30:31], s[64:65], v17, s74, v[22:23]
	global_load_dword v70, v[30:31], off nt
.LBB0_730:
	s_or_b64 exec, exec, s[0:1]
	s_and_saveexec_b64 s[0:1], vcc
	s_cbranch_execz .LBB0_732
	v_or_b32_e32 v17, 50, v16
	v_mad_i64_i32 v[30:31], s[64:65], v17, s74, v[22:23]
	global_load_dword v68, v[30:31], off nt
.LBB0_732:
	s_or_b64 exec, exec, s[0:1]
	v_mov_b32_e32 v71, 0
	v_mov_b32_e32 v72, 0
	s_and_saveexec_b64 s[0:1], vcc
	s_cbranch_execz .LBB0_734
	v_or_b32_e32 v17, 52, v16
	v_mad_i64_i32 v[30:31], s[64:65], v17, s74, v[22:23]
	global_load_dword v72, v[30:31], off nt
.LBB0_734:
	s_or_b64 exec, exec, s[0:1]
	s_and_saveexec_b64 s[0:1], vcc
	s_cbranch_execz .LBB0_736
	v_or_b32_e32 v17, 54, v16
	v_mad_i64_i32 v[30:31], s[64:65], v17, s74, v[22:23]
	global_load_dword v71, v[30:31], off nt
.LBB0_736:
	s_or_b64 exec, exec, s[0:1]
	v_mov_b32_e32 v31, 0
	v_mov_b32_e32 v30, 0
	s_and_saveexec_b64 s[0:1], vcc
	s_cbranch_execz .LBB0_738
	v_or_b32_e32 v17, 56, v16
	v_mad_i64_i32 v[32:33], s[64:65], v17, s74, v[22:23]
	global_load_dword v30, v[32:33], off nt
.LBB0_738:
	s_or_b64 exec, exec, s[0:1]
	s_and_saveexec_b64 s[0:1], vcc
	s_cbranch_execz .LBB0_740
	v_or_b32_e32 v17, 58, v16
	v_mad_i64_i32 v[32:33], s[64:65], v17, s74, v[22:23]
	global_load_dword v31, v[32:33], off nt
.LBB0_740:
	s_or_b64 exec, exec, s[0:1]
	v_mov_b32_e32 v33, 0
	v_mov_b32_e32 v32, 0
	s_and_saveexec_b64 s[0:1], vcc
	s_cbranch_execz .LBB0_742
	v_or_b32_e32 v17, 60, v16
	v_mad_i64_i32 v[78:79], s[64:65], v17, s74, v[22:23]
	global_load_dword v32, v[78:79], off nt
.LBB0_742:
	s_or_b64 exec, exec, s[0:1]
	s_and_saveexec_b64 s[0:1], vcc
	s_cbranch_execz .LBB0_744
	v_or_b32_e32 v17, 62, v16
	v_mad_i64_i32 v[22:23], s[64:65], v17, s74, v[22:23]
	global_load_dword v33, v[22:23], off nt
.LBB0_744:
	s_or_b64 exec, exec, s[0:1]
	v_cndmask_b32_e64 v17, 0, 1, s[52:53]
	v_cmp_ne_u32_e64 s[0:1], 1, v17
	s_andn2_b64 vcc, exec, s[52:53]
	v_add_u32_e32 v73, v35, v37
	s_cbranch_vccnz .LBB0_764
	v_ashrrev_i32_e32 v17, 31, v16
	s_ashr_i32 s63, s62, 31
	v_lshl_add_u64 v[16:17], v[16:17], 2, s[56:57]
	v_lshl_add_u64 v[22:23], s[62:63], 0, v[6:7]
	v_lshl_add_u64 v[22:23], v[22:23], 2, s[56:57]
	global_load_dword v80, v[16:17], off nt
	global_load_dword v81, v[22:23], off offset:8 nt
	global_load_dword v82, v[22:23], off offset:16 nt
	global_load_dword v83, v[22:23], off offset:24 nt
	s_nop 0
	global_load_dword v16, v[22:23], off offset:32 nt
	global_load_dword v17, v[22:23], off offset:40 nt
	global_load_dword v78, v[22:23], off offset:48 nt
	global_load_dword v79, v[22:23], off offset:56 nt
	s_waitcnt vmcnt(7)
	v_mul_f32_e32 v22, v58, v80
	s_waitcnt vmcnt(6)
	v_mul_f32_e32 v80, v8, v81
	s_waitcnt vmcnt(5)
	v_mul_f32_e32 v81, v62, v82
	ds_write_b32 v36, v22
	s_waitcnt vmcnt(4)
	v_mul_f32_e32 v82, v59, v83
	s_waitcnt vmcnt(2)
	v_pk_mul_f32 v[16:17], v[14:15], v[16:17]
	ds_write2_b32 v73, v80, v81 offset1:66
	ds_write_b32 v73, v82 offset:528
	s_waitcnt vmcnt(0)
	v_pk_mul_f32 v[22:23], v[18:19], v[78:79]
	s_cbranch_execnz .LBB0_747

; template <int MAP> __device__ __forceinline__ void transpose_item(const float* __restrict__ W, const float* __restrict__ gk, int K, int N, u16* __restrict__ WT, LAS float* scr, int item, int lane) {
;     ...
; #pragma unroll
;     for (int i = 0; i < 32; ++i) { const int kk = 2 * i + (lane >> 5); float w = wv[i]; if (gk) w *= gk[k0 + kk]; scr[kk * 33 + (lane & 31)] = w; }
.LBB0_747:
	s_waitcnt vmcnt(0)
	v_add_u32_e32 v8, v35, v38
	ds_write2_b32 v8, v16, v17 offset1:66
	ds_write2_b32 v8, v22, v23 offset0:132 offset1:198
	s_and_b64 vcc, exec, s[0:1]
	v_add_u32_e32 v8, v35, v39
	s_cbranch_vccnz .LBB0_765
	s_ashr_i32 s63, s62, 31
	v_lshl_add_u64 v[14:15], s[62:63], 0, v[6:7]
	v_lshl_add_u64 v[14:15], v[14:15], 2, s[56:57]
	global_load_dword v22, v[14:15], off offset:64 nt
	global_load_dword v23, v[14:15], off offset:72 nt
	global_load_dword v58, v[14:15], off offset:80 nt
	global_load_dword v59, v[14:15], off offset:88 nt
	global_load_dword v16, v[14:15], off offset:96 nt
	global_load_dword v17, v[14:15], off offset:104 nt
	global_load_dword v18, v[14:15], off offset:112 nt
	global_load_dword v19, v[14:15], off offset:120 nt
	s_waitcnt vmcnt(7)
	v_mul_f32_e32 v22, v61, v22
	s_waitcnt vmcnt(6)
	v_mul_f32_e32 v23, v60, v23
	s_waitcnt vmcnt(5)
	v_mul_f32_e32 v58, v65, v58
	s_waitcnt vmcnt(4)
	v_mul_f32_e32 v59, v63, v59
	ds_write2_b32 v8, v22, v23 offset1:66
	ds_write2_b32 v8, v58, v59 offset0:132 offset1:198
	s_waitcnt vmcnt(2)
	v_pk_mul_f32 v[14:15], v[20:21], v[16:17]
	s_waitcnt vmcnt(0)
	v_pk_mul_f32 v[16:17], v[24:25], v[18:19]
	s_cbranch_execnz .LBB0_750

; template <int MAP> __device__ __forceinline__ void transpose_item(const float* __restrict__ W, const float* __restrict__ gk, int K, int N, u16* __restrict__ WT, LAS float* scr, int item, int lane) {
;     ...
; #pragma unroll
;     for (int i = 0; i < 32; ++i) { const int kk = 2 * i + (lane >> 5); float w = wv[i]; if (gk) w *= gk[k0 + kk]; scr[kk * 33 + (lane & 31)] = w; }
.LBB0_750:
	v_add_u32_e32 v8, v35, v40
	ds_write2_b32 v8, v14, v15 offset1:66
	ds_write2_b32 v8, v16, v17 offset0:132 offset1:198
	s_and_b64 vcc, exec, s[0:1]
	v_add_u32_e32 v8, v35, v41
	s_cbranch_vccnz .LBB0_766
	s_ashr_i32 s63, s62, 31
	v_lshl_add_u64 v[14:15], s[62:63], 0, v[6:7]
	v_lshl_add_u64 v[14:15], v[14:15], 2, s[56:57]
	global_load_dword v20, v[14:15], off offset:128 nt
	global_load_dword v21, v[14:15], off offset:136 nt
	global_load_dword v22, v[14:15], off offset:144 nt
	global_load_dword v23, v[14:15], off offset:152 nt
	global_load_dword v16, v[14:15], off offset:160 nt
	global_load_dword v17, v[14:15], off offset:168 nt
	global_load_dword v18, v[14:15], off offset:176 nt
	global_load_dword v19, v[14:15], off offset:184 nt
	s_waitcnt vmcnt(7)
	v_mul_f32_e32 v20, v66, v20
	s_waitcnt vmcnt(6)
	v_mul_f32_e32 v21, v64, v21
	s_waitcnt vmcnt(5)
	v_mul_f32_e32 v22, v69, v22
	s_waitcnt vmcnt(4)
	v_mul_f32_e32 v23, v67, v23
	ds_write2_b32 v8, v20, v21 offset1:66
	ds_write2_b32 v8, v22, v23 offset0:132 offset1:198
	s_waitcnt vmcnt(2)
	v_pk_mul_f32 v[14:15], v[26:27], v[16:17]
	s_waitcnt vmcnt(0)
	v_pk_mul_f32 v[16:17], v[28:29], v[18:19]
	s_cbranch_execnz .LBB0_753

; template <int MAP> __device__ __forceinline__ void transpose_item(const float* __restrict__ W, const float* __restrict__ gk, int K, int N, u16* __restrict__ WT, LAS float* scr, int item, int lane) {
;     ...
; #pragma unroll
;     for (int i = 0; i < 32; ++i) { const int kk = 2 * i + (lane >> 5); float w = wv[i]; if (gk) w *= gk[k0 + kk]; scr[kk * 33 + (lane & 31)] = w; }
.LBB0_753:
	v_add_u32_e32 v8, v35, v42
	ds_write2_b32 v8, v14, v15 offset1:66
	ds_write2_b32 v8, v16, v17 offset0:132 offset1:198
	s_and_b64 vcc, exec, s[0:1]
	v_add_u32_e32 v8, v35, v43
	s_cbranch_vccnz .LBB0_767
	s_ashr_i32 s63, s62, 31
	v_lshl_add_u64 v[14:15], s[62:63], 0, v[6:7]
	v_lshl_add_u64 v[14:15], v[14:15], 2, s[56:57]
	global_load_dword v20, v[14:15], off offset:192 nt
	global_load_dword v21, v[14:15], off offset:200 nt
	global_load_dword v22, v[14:15], off offset:208 nt
	global_load_dword v23, v[14:15], off offset:216 nt
	global_load_dword v16, v[14:15], off offset:224 nt
	global_load_dword v17, v[14:15], off offset:232 nt
	global_load_dword v18, v[14:15], off offset:240 nt
	global_load_dword v19, v[14:15], off offset:248 nt
	s_waitcnt vmcnt(7)
	v_mul_f32_e32 v20, v70, v20
	s_waitcnt vmcnt(6)
	v_mul_f32_e32 v21, v68, v21
	s_waitcnt vmcnt(5)
	v_mul_f32_e32 v22, v72, v22
	s_waitcnt vmcnt(4)
	v_mul_f32_e32 v23, v71, v23
	ds_write2_b32 v8, v20, v21 offset1:66
	ds_write2_b32 v8, v22, v23 offset0:132 offset1:198
	s_waitcnt vmcnt(2)
	v_pk_mul_f32 v[14:15], v[30:31], v[16:17]
	s_waitcnt vmcnt(0)
	v_pk_mul_f32 v[16:17], v[32:33], v[18:19]
	s_cbranch_execnz .LBB0_756

; #define LAS __attribute__((address_space(3)))
; template <int MAP> __device__ __forceinline__ void transpose_item(const float* __restrict__ W, const float* __restrict__ gk, int K, int N, u16* __restrict__ WT, LAS float* scr, int item, int lane) {
;     const int nblk = (N + 31) >> 5, kb = item / nblk, nb = item - kb * nblk, k0 = 64 * kb, n0 = 32 * nb;
;     const int nn = n0 + (lane & 31); const bool ok = nn < N;
;     float wv[32];
; #pragma unroll
;     for (int i = 0; i < 32; ++i) { const int kk = 2 * i + (lane >> 5); wv[i] = ok ? W[(size_t)(k0 + kk) * N + nn] : 0.f; }
.LBB0_771:
	s_ashr_i32 s22, s58, 31
	s_lshr_b32 s22, s22, 27
	s_add_i32 s22, s58, s22
	s_ashr_i32 s56, s22, 5
	s_lshl_b32 s57, s56, 10
	s_sub_i32 s22, s60, s57
	v_add_u32_e32 v14, s22, v34
	v_ashrrev_i32_e32 v15, 31, v14
	v_cmp_gt_i32_e32 vcc, s79, v14
	v_lshl_or_b32 v16, s56, 6, v6
	v_lshl_add_u64 v[14:15], v[14:15], 2, s[0:1]
	v_mov_b32_e32 v18, 0
	v_mov_b32_e32 v8, 0
	s_and_saveexec_b64 s[22:23], vcc
	s_cbranch_execz .LBB0_773
	v_ashrrev_i32_e32 v17, 31, v16
	v_lshlrev_b64 v[20:21], 12, v[16:17]
	v_lshl_add_u64 v[20:21], v[14:15], 0, v[20:21]
	global_load_dword v8, v[20:21], off nt

; __device__ __forceinline__ unsigned pk2(float lo, float hi) { const f32x2_ v = {lo, hi}; const bf16x2_ b = __builtin_convertvector(v, bf16x2_); return __builtin_bit_cast(unsigned, b); }
; __device__ __forceinline__ float wave_sum(float v, int lane) { return lane63_(wave_incl_sum(v, lane)); }
; __device__ __forceinline__ size_t tl(int row, int col, int K) { return (size_t)(row >> 8) * ((size_t)256 * K) + (size_t)(col >> 6) * (256 * 64) + (size_t)((row & 255) * 64 + (col & 63)); }
; __device__ __forceinline__ void prologue(const Args& A, unsigned char* ws, LAS unsigned char* lds, int gw, int NGW, int wave, int lane) {
;     ...
;     for (int row = gw; row < MROWS; row += NGW) {
;         const v4f* xr = (const v4f*)(x + (size_t)row * DM) + lane; v4f v[4]; float s = 0.f;
; #pragma unroll
;         for (int j = 0; j < 4; ++j) { v[j] = xr[64 * j]; s += (v[j].x * v[j].x + v[j].y * v[j].y) + (v[j].z * v[j].z + v[j].w * v[j].w); }
;         s = wave_sum(s, lane);
; #pragma unroll
;         for (int j = 0; j < 4; ++j) { v2u w; w.x = pk2(v[j].x, v[j].y); w.y = pk2(v[j].z, v[j].w); *(v2u*)(xb + tl(row, 4 * lane + 256 * j, DM)) = w; }
;         if (lane < 16) ssp[(size_t)row * 16 + lane] = lane == 0 ? s : 0.f;
.LBB0_850:
	global_load_dwordx4 v[18:21], v[10:11], off nt
	global_load_dwordx4 v[22:25], v[10:11], off offset:1024 nt
	global_load_dwordx4 v[26:29], v[10:11], off offset:2048 nt
	global_load_dwordx4 v[30:33], v[10:11], off offset:3072 nt
	s_ashr_i32 s0, s30, 8
	s_and_b32 s8, s22, 0x3fc0
	s_ashr_i32 s1, s0, 31
	v_or_b32_e32 v6, s8, v12
	s_lshl_b64 s[0:1], s[0:1], 19
	v_lshlrev_b32_e32 v6, 1, v6
	v_lshl_add_u64 v[34:35], v[4:5], 0, s[0:1]
	v_lshl_add_u64 v[34:35], v[34:35], 0, v[6:7]
	v_mov_b32_e32 v50, 0
	v_add_co_u32_e32 v36, vcc, s23, v34
	v_mov_b32_e32 v51, 0
	s_nop 0
	v_addc_co_u32_e32 v37, vcc, 0, v35, vcc
	v_add_co_u32_e32 v38, vcc, s27, v34
	s_waitcnt vmcnt(3)
	v_mul_f32_e32 v6, v19, v19
	v_mul_f32_e32 v52, v21, v21
	s_waitcnt vmcnt(2)
	v_mul_f32_e32 v53, v23, v23
	v_mul_f32_e32 v54, v25, v25
	s_waitcnt vmcnt(1)
	v_mul_f32_e32 v55, v27, v27
	v_mul_f32_e32 v56, v29, v29
	v_fmac_f32_e32 v6, v18, v18
	v_fmac_f32_e32 v52, v20, v20
	v_fmac_f32_e32 v53, v22, v22
	v_fmac_f32_e32 v54, v24, v24
	s_waitcnt vmcnt(0)
	v_mul_f32_e32 v57, v31, v31
	v_mul_f32_e32 v58, v33, v33
	v_cvt_pk_bf16_f32 v42, v18, v19
	v_fmac_f32_e32 v55, v26, v26
	v_fmac_f32_e32 v56, v28, v28
	v_add_f32_e32 v6, v6, v52
	v_add_f32_e32 v18, v53, v54
	v_fmac_f32_e32 v57, v30, v30
	v_fmac_f32_e32 v58, v32, v32
	v_add_f32_e32 v19, v55, v56
	v_add_f32_e32 v6, v6, v18
	v_cvt_pk_bf16_f32 v43, v20, v21
	v_add_f32_e32 v20, v57, v58
	v_add_f32_e32 v6, v6, v19
	v_add_f32_e32 v6, v6, v20
	v_addc_co_u32_e32 v39, vcc, 0, v35, vcc
	s_nop 0
	v_add_f32_dpp v6, v6, v6 row_shr:1 row_mask:0xf bank_mask:0xf bound_ctrl:1
	v_add_co_u32_e32 v40, vcc, 0x60000, v34
	s_nop 0
	v_add_f32_dpp v6, v6, v6 row_shr:2 row_mask:0xf bank_mask:0xf bound_ctrl:1
	v_addc_co_u32_e32 v41, vcc, 0, v35, vcc
	s_nop 0
	v_add_f32_dpp v6, v6, v6 row_shr:4 row_mask:0xf bank_mask:0xf bound_ctrl:1
	v_cvt_pk_bf16_f32 v48, v30, v31
	v_cvt_pk_bf16_f32 v49, v32, v33
	v_add_f32_dpp v6, v6, v6 row_shr:8 row_mask:0xf bank_mask:0xf bound_ctrl:1
	v_cvt_pk_bf16_f32 v44, v22, v23
	v_cvt_pk_bf16_f32 v45, v24, v25
	v_mov_b32_dpp v50, v6 row_bcast:15 row_mask:0xa bank_mask:0xf
	v_add_f32_e32 v6, v6, v50
	v_cvt_pk_bf16_f32 v46, v26, v27
	v_cvt_pk_bf16_f32 v47, v28, v29
	v_mov_b32_dpp v51, v6 row_bcast:31 row_mask:0xc bank_mask:0xf
	v_add_f32_e32 v6, v6, v51
	global_store_dwordx2 v[34:35], v[42:43], off
	global_store_dwordx2 v[36:37], v[44:45], off
	global_store_dwordx2 v[38:39], v[46:47], off
	v_readlane_b32 s8, v6, 63
	global_store_dwordx2 v[40:41], v[48:49], off
	s_and_saveexec_b64 s[0:1], s[4:5]
	s_cbranch_execz .LBB0_852
	v_mov_b32_e32 v6, s8
	v_cndmask_b32_e64 v6, 0, v6, s[6:7]
	global_store_dword v[8:9], v6, off
